# v106 + W_fc1 transpose: g_mlp row-scale values loaded once per workgroup before the tile loop (was one serial L2 round trip per tile)
# speedup vs baseline: 1.0077x; 1.0012x over previous
.LBB0_340:
	v_readlane_b32 s0, v253, 42
	v_readlane_b32 s1, v253, 43
	v_mov_b32_e32 v0, v179
	s_andn2_b64 vcc, exec, s[0:1]
	v_cndmask_b32_e64 v1, 0, 1, s[0:1]
	v_cmp_ne_u32_e64 s[40:41], 1, v1
	s_cbranch_vccnz .LBB0_361
	v_ashrrev_i32_e32 v17, 4, v0
	v_readlane_b32 s0, v253, 44
	v_lshlrev_b32_e32 v1, 2, v0
	s_load_dword s6, s[74:75], 0x0
	v_lshlrev_b32_e32 v48, 3, v0
	s_and_b32 s7, s96, 15
	v_and_b32_e32 v48, 56, v48
	s_lshl_b32 s7, s7, 6
	v_or_b32_e32 v48, s7, v48
	v_lshlrev_b32_e32 v48, 2, v48
	s_cmp_lg_u64 s[90:91], 0
	s_cbranch_scc0 .Lks_none
	global_load_dwordx4 v[40:43], v48, s[90:91] offset:16
	global_load_dwordx4 v[44:47], v48, s[90:91]
.Lks_none:
	s_waitcnt lgkmcnt(0)
	s_and_b32 s6, s6, 15
	v_writelane_b32 v255, s6, 62
	v_and_b32_e32 v4, 60, v1
	v_add_u32_e32 v2, s0, v17
	v_ashrrev_i32_e32 v3, 31, v2
	v_readlane_b32 s0, v253, 51
	v_lshlrev_b64 v[2:3], 14, v[2:3]
	v_readlane_b32 s1, v253, 52
	v_lshlrev_b32_e32 v176, 2, v4
	v_ashrrev_i32_e32 v32, 3, v0
	v_lshl_add_u64 v[2:3], s[0:1], 0, v[2:3]
	v_lshl_add_u64 v[2:3], v[2:3], 0, v[176:177]
	v_add_co_u32_e32 v6, vcc, 0x80000, v2
	s_movk_i32 s0, 0x104
	s_nop 0
	v_addc_co_u32_e32 v7, vcc, 0, v3, vcc
	global_load_dwordx4 v[8:11], v[2:3], off
	global_load_dwordx4 v[12:15], v[6:7], off
	v_lshlrev_b32_e32 v0, 3, v0
	v_mul_lo_u32 v1, v17, s0
	v_and_b32_e32 v16, 56, v0
	v_add3_u32 v25, 0, v1, v176
	v_lshl_add_u32 v0, v32, 2, 0
	v_xor_b32_e32 v33, 32, v32
	v_mul_u32_u24_e32 v1, 0x104, v16
	v_cmp_lt_i32_e64 s[42:43], 32, v32
	v_mad_u32_u24 v34, v16, s0, 0
	v_lshlrev_b32_e32 v35, 1, v33
	v_lshlrev_b32_e32 v36, 1, v32
	v_lshlrev_b32_e32 v18, 2, v4
	v_add_u32_e32 v37, v0, v1
	s_mov_b32 s3, s96
	s_branch .LBB0_343

.LBB0_359:
	s_ashr_i32 s6, s3, 31
	s_lshr_b32 s6, s6, 28
	s_add_i32 s6, s3, s6
	s_and_b32 s7, s6, 0x3fffff0
	v_readlane_b32 s20, v253, 53
	s_sub_i32 s3, s3, s7
	v_readlane_b32 s21, v253, 54
	s_andn2_b64 vcc, exec, s[20:21]
	s_lshl_b32 s28, s3, 6
	s_cbranch_vccnz .LBB0_342
	v_readlane_b32 s20, v255, 62
	s_waitcnt lgkmcnt(0)
	s_cmp_eq_u32 s20, 0
	s_cbranch_scc0 .Lks_slow
	v_pk_mul_f32 v[6:7], v[6:7], v[42:43]
	v_pk_mul_f32 v[2:3], v[2:3], v[46:47]
	v_pk_mul_f32 v[4:5], v[4:5], v[40:41]
	v_pk_mul_f32 v[0:1], v[0:1], v[44:45]
	s_branch .LBB0_342
.Lks_slow:
	v_or_b32_e32 v20, s28, v16
	v_ashrrev_i32_e32 v21, 31, v20
	v_lshl_add_u64 v[26:27], v[20:21], 2, s[90:91]
	global_load_dwordx4 v[20:23], v[26:27], off offset:16
	s_nop 0
	global_load_dwordx4 v[26:29], v[26:27], off
	s_waitcnt vmcnt(1) lgkmcnt(0)
	v_pk_mul_f32 v[6:7], v[6:7], v[22:23]
	s_waitcnt vmcnt(0)
	v_pk_mul_f32 v[2:3], v[2:3], v[28:29]
	v_pk_mul_f32 v[4:5], v[4:5], v[20:21]
	v_pk_mul_f32 v[0:1], v[0:1], v[26:27]
	s_branch .LBB0_342
